# A' loads one h1 segment per lane-group and broadcasts through LDS (fewer VMEM instructions)
# speedup vs baseline: 1.1035x; 1.0060x over previous
.LBB0_1385:
	s_mov_b64 exec, -1
	s_nop 3
	v_readfirstlane_b32 s20, v174
	s_load_dwordx4 s[4:7], s[52:53], 0x120
	s_load_dwordx2 s[8:9], s[52:53], 0xa0
	s_load_dwordx2 s[10:11], s[52:53], 0x68
	s_load_dwordx2 s[12:13], s[52:53], 0x108
	s_load_dwordx2 s[14:15], s[52:53], 0x140
	s_load_dwordx2 s[16:17], s[52:53], 0x60
	s_load_dwordx2 s[48:49], s[52:53], 0x98
	s_load_dwordx2 s[78:79], s[52:53], 0x100
	s_load_dwordx2 s[54:55], s[52:53], 0x118
	s_load_dwordx2 s[56:57], s[52:53], 0x38
	s_load_dwordx2 s[58:59], s[52:53], 0xa8
	s_load_dwordx2 s[76:77], s[52:53], 0xb0
	s_and_b32 s21, s20, 3
	s_lshr_b32 s22, s20, 2
	s_and_b32 s23, s22, 7
	s_lshr_b32 s24, s22, 3
	s_lshl_b32 s24, s24, 2
	s_add_u32 s24, s24, s21
	s_lshr_b32 s25, s80, 2
	s_lshl_b32 s43, s23, 2
	s_movk_i32 s19, 0xc0
	v_mbcnt_lo_u32_b32 v0, -1, 0
	v_mbcnt_hi_u32_b32 v0, -1, v0
	v_and_b32_e32 v10, 7, v0
	v_lshrrev_b32_e32 v11, 3, v0
	v_lshlrev_b32_e32 v1, 4, v10
	v_lshlrev_b32_e32 v2, 6, v11
	v_mov_b32_e32 v3, 0
	s_mul_i32 s29, s21, 0x2400
	v_mul_u32_u24_e32 v4, 0x90, v0
	v_add_u32_e32 v4, s29, v4
	v_mul_u32_u24_e32 v5, 0x90, v10
	v_lshl_add_u32 v5, v11, 4, v5
	v_add_u32_e32 v5, s29, v5
	v_lshlrev_b32_e32 v6, 10, v11
	v_lshl_add_u32 v6, v10, 4, v6
	s_lshl_b32 s29, s23, 7
	v_add_u32_e32 v6, s29, v6
	v_cmp_eq_u32_e64 s[36:37], 63, v0
	s_waitcnt lgkmcnt(0)
	s_mul_i32 s29, s23, 0x300000
	s_add_u32 s26, s8, s29
	s_addc_u32 s27, s9, 0
	s_add_u32 s48, s48, s29
	s_addc_u32 s49, s49, 0
	s_lshl_b32 s29, s23, 9
	s_add_u32 s50, s78, s29
	s_addc_u32 s51, s79, 0
	v_cmp_eq_u32_e64 s[60:61], 0, v10
	v_cmp_eq_u32_e64 s[62:63], 1, v10
	v_cmp_eq_u32_e64 s[64:65], 2, v10
	v_cmp_eq_u32_e64 s[66:67], 3, v10
	v_cmp_eq_u32_e64 s[68:69], 4, v10
	v_cmp_eq_u32_e64 s[70:71], 5, v10
	v_cmp_eq_u32_e64 s[72:73], 6, v10
	v_cmp_eq_u32_e64 s[74:75], 7, v10
	v_lshlrev_b32_e32 v9, 2, v10
	v_lshl_add_u32 v9, v11, 6, v9
	s_lshl_b32 s29, s23, 7
	v_mov_b32_e32 v15, v6
	global_load_dwordx4 v[112:115], v15, s[56:57]
	s_mul_i32 s29, s21, 0x2400
	v_mul_u32_u24_e32 v12, 0x90, v10
	v_add_u32_e32 v12, s29, v12
	v_lshl_add_u32 v15, v11, 4, v12
	s_waitcnt vmcnt(0)
	ds_write_b128 v15, v[112:115]
	s_waitcnt lgkmcnt(0)
	v_mov_b32_e32 v124, v12
	v_add_u32_e32 v14, 0x480, v12
	v_add_u32_e32 v13, 0x480, v15
	v_lshlrev_b32_e32 v125, 3, v10
	v_add_u32_e32 v125, 0x200000, v125
	s_mov_b32 s28, 0
	s_add_u32 s40, s28, 0
	s_min_u32 s40, s40, 127
	s_lshl_b32 s40, s40, 8
	s_add_u32 s40, s40, s24
	s_lshl_b32 s29, s40, 13
	s_add_u32 s34, s10, s29
	s_addc_u32 s35, s11, 0
	global_load_dwordx4 v[48:51], v6, s[34:35]
	s_lshl_b32 s29, s40, 7
	s_add_u32 s38, s54, s29
	s_addc_u32 s39, s55, 0
	global_load_dwordx4 v[112:115], v1, s[38:39]
	s_add_u32 s40, s28, 0
	s_min_u32 s40, s40, 127
	s_lshl_b32 s40, s40, 8
	s_add_u32 s40, s40, s24
	s_lshl_b32 s29, s40, 9
	s_add_u32 s30, s4, s29
	s_addc_u32 s31, s5, 0
	global_load_dwordx4 v[16:19], v2, s[30:31] offset:0
	global_load_dwordx4 v[20:23], v2, s[30:31] offset:16
	global_load_dwordx4 v[24:27], v2, s[30:31] offset:32
	global_load_dwordx4 v[28:31], v2, s[30:31] offset:48
	s_add_u32 s40, s28, 1
	s_min_u32 s40, s40, 127
	s_lshl_b32 s40, s40, 8
	s_add_u32 s40, s40, s24
	s_lshl_b32 s29, s40, 9
	s_add_u32 s30, s4, s29
	s_addc_u32 s31, s5, 0
	global_load_dwordx4 v[32:35], v2, s[30:31] offset:0
	global_load_dwordx4 v[36:39], v2, s[30:31] offset:16
	global_load_dwordx4 v[40:43], v2, s[30:31] offset:32
	global_load_dwordx4 v[44:47], v2, s[30:31] offset:48
	s_waitcnt vmcnt(0)
	v_lshl_add_u32 v7, v16, 7, v1
	v_lshl_add_u32 v8, v16, 6, v125
	global_load_dwordx4 v[160:163], v7, s[48:49] sc1
	global_load_dwordx2 v[164:165], v8, s[48:49] sc1
	v_lshl_add_u32 v7, v17, 7, v1
	v_lshl_add_u32 v8, v17, 6, v125
	global_load_dwordx4 v[166:169], v7, s[48:49] sc1
	global_load_dwordx2 v[170:171], v8, s[48:49] sc1
	v_lshl_add_u32 v7, v18, 7, v1
	v_lshl_add_u32 v8, v18, 6, v125
	global_load_dwordx4 v[172:175], v7, s[48:49] sc1
	global_load_dwordx2 v[176:177], v8, s[48:49] sc1
	v_lshl_add_u32 v7, v19, 7, v1
	v_lshl_add_u32 v8, v19, 6, v125
	global_load_dwordx4 v[178:181], v7, s[48:49] sc1
	global_load_dwordx2 v[182:183], v8, s[48:49] sc1
	v_lshl_add_u32 v7, v20, 7, v1
	v_lshl_add_u32 v8, v20, 6, v125
	global_load_dwordx4 v[184:187], v7, s[48:49] sc1
	global_load_dwordx2 v[188:189], v8, s[48:49] sc1
	v_lshl_add_u32 v7, v21, 7, v1
	v_lshl_add_u32 v8, v21, 6, v125
	global_load_dwordx4 v[190:193], v7, s[48:49] sc1
	global_load_dwordx2 v[194:195], v8, s[48:49] sc1
	v_lshl_add_u32 v7, v22, 7, v1
	v_lshl_add_u32 v8, v22, 6, v125
	global_load_dwordx4 v[196:199], v7, s[48:49] sc1
	global_load_dwordx2 v[200:201], v8, s[48:49] sc1
	v_lshl_add_u32 v7, v23, 7, v1
	v_lshl_add_u32 v8, v23, 6, v125
	global_load_dwordx4 v[202:205], v7, s[48:49] sc1
	global_load_dwordx2 v[206:207], v8, s[48:49] sc1
	v_lshl_add_u32 v7, v24, 7, v1
	v_lshl_add_u32 v8, v24, 6, v125
	global_load_dwordx4 v[208:211], v7, s[48:49] sc1
	global_load_dwordx2 v[212:213], v8, s[48:49] sc1
	v_lshl_add_u32 v7, v25, 7, v1
	v_lshl_add_u32 v8, v25, 6, v125
	global_load_dwordx4 v[214:217], v7, s[48:49] sc1
	global_load_dwordx2 v[218:219], v8, s[48:49] sc1
	v_lshl_add_u32 v7, v26, 7, v1
	v_lshl_add_u32 v8, v26, 6, v125
	global_load_dwordx4 v[220:223], v7, s[48:49] sc1
	global_load_dwordx2 v[224:225], v8, s[48:49] sc1
	v_lshl_add_u32 v7, v27, 7, v1
	v_lshl_add_u32 v8, v27, 6, v125
	global_load_dwordx4 v[226:229], v7, s[48:49] sc1
	global_load_dwordx2 v[230:231], v8, s[48:49] sc1
	v_lshl_add_u32 v7, v28, 7, v1
	v_lshl_add_u32 v8, v28, 6, v125
	global_load_dwordx4 v[232:235], v7, s[48:49] sc1
	global_load_dwordx2 v[236:237], v8, s[48:49] sc1
	v_lshl_add_u32 v7, v29, 7, v1
	v_lshl_add_u32 v8, v29, 6, v125
	global_load_dwordx4 v[238:241], v7, s[48:49] sc1
	global_load_dwordx2 v[242:243], v8, s[48:49] sc1
	v_lshl_add_u32 v7, v30, 7, v1
	v_lshl_add_u32 v8, v30, 6, v125
	global_load_dwordx4 v[244:247], v7, s[48:49] sc1
	global_load_dwordx2 v[248:249], v8, s[48:49] sc1
	v_lshl_add_u32 v7, v31, 7, v1
	v_lshl_add_u32 v8, v31, 6, v125
	global_load_dwordx4 v[250:253], v7, s[48:49] sc1
	global_load_dwordx2 v[254:255], v8, s[48:49] sc1
	global_store_dword v3, v3, s[14:15] offset:480
	global_store_dword v3, v3, s[14:15] offset:484
.Lpa_tokloop:
	s_waitcnt vmcnt(34)
	ds_write_b128 v13, v[48:51]
	ds_read_b128 v[128:131], v124 offset:0
	ds_read_b128 v[132:135], v124 offset:16
	ds_read_b128 v[136:139], v124 offset:32
	ds_read_b128 v[140:143], v124 offset:48
	ds_read_b128 v[144:147], v124 offset:64
	ds_read_b128 v[148:151], v124 offset:80
	ds_read_b128 v[152:155], v124 offset:96
	ds_read_b128 v[156:159], v124 offset:112
	ds_read_b128 v[48:51], v14 offset:0
	ds_read_b128 v[52:55], v14 offset:16
	ds_read_b128 v[56:59], v14 offset:32
	ds_read_b128 v[60:63], v14 offset:48
	ds_read_b128 v[64:67], v14 offset:64
	ds_read_b128 v[68:71], v14 offset:80
	ds_read_b128 v[72:75], v14 offset:96
	ds_read_b128 v[76:79], v14 offset:112
	v_add_f32_e32 v126, v112, v113
	v_add_f32_e32 v127, v114, v115
	v_add_f32_e32 v126, v126, v127
	s_nop 1
	v_add_f32_dpp v126, v126, v126 quad_perm:[1,0,3,2] row_mask:0xf bank_mask:0xf
	s_nop 1
	v_add_f32_dpp v126, v126, v126 quad_perm:[2,3,0,1] row_mask:0xf bank_mask:0xf
	s_nop 1
	v_add_f32_dpp v126, v126, v126 row_half_mirror row_mask:0xf bank_mask:0xf
	s_nop 1
	v_mov_b32_e32 v127, 0x358637bd
	v_fmac_f32_e32 v127, 0x3a000000, v126
	v_rsq_f32_e32 v127, v127
	s_waitcnt lgkmcnt(0)
	v_pk_mul_f32 v[80:81], v[48:49], v[128:129]
	v_pk_mul_f32 v[82:83], v[50:51], v[130:131]
	v_pk_mul_f32 v[84:85], v[52:53], v[132:133]
	v_pk_mul_f32 v[86:87], v[54:55], v[134:135]
	v_pk_mul_f32 v[88:89], v[56:57], v[136:137]
	v_pk_mul_f32 v[90:91], v[58:59], v[138:139]
	v_pk_mul_f32 v[92:93], v[60:61], v[140:141]
	v_pk_mul_f32 v[94:95], v[62:63], v[142:143]
	v_pk_mul_f32 v[96:97], v[64:65], v[144:145]
	v_pk_mul_f32 v[98:99], v[66:67], v[146:147]
	v_pk_mul_f32 v[100:101], v[68:69], v[148:149]
	v_pk_mul_f32 v[102:103], v[70:71], v[150:151]
	v_pk_mul_f32 v[104:105], v[72:73], v[152:153]
	v_pk_mul_f32 v[106:107], v[74:75], v[154:155]
	v_pk_mul_f32 v[108:109], v[76:77], v[156:157]
	v_pk_mul_f32 v[110:111], v[78:79], v[158:159]
	s_add_u32 s40, s28, 0
	s_min_u32 s40, s40, 127
	s_lshl_b32 s40, s40, 8
	s_add_u32 s40, s40, s24
	s_lshl_b32 s29, s40, 12
	s_add_u32 s44, s50, s29
	s_addc_u32 s45, s51, 0
	s_add_u32 s40, s28, 1
	s_min_u32 s40, s40, 127
	s_lshl_b32 s40, s40, 8
	s_add_u32 s40, s40, s24
	s_lshl_b32 s29, s40, 13
	s_add_u32 s34, s10, s29
	s_addc_u32 s35, s11, 0
	global_load_dwordx4 v[48:51], v6, s[34:35]
	s_lshl_b32 s29, s40, 7
	s_add_u32 s38, s54, s29
	s_addc_u32 s39, s55, 0
	global_load_dwordx4 v[112:115], v1, s[38:39]
	s_add_u32 s40, s28, 2
	s_min_u32 s40, s40, 127
	s_lshl_b32 s40, s40, 8
	s_add_u32 s40, s40, s24
	s_lshl_b32 s29, s40, 9
	s_add_u32 s30, s4, s29
	s_addc_u32 s31, s5, 0
	global_load_dwordx4 v[16:19], v2, s[30:31] offset:0
	global_load_dwordx4 v[20:23], v2, s[30:31] offset:16
	global_load_dwordx4 v[24:27], v2, s[30:31] offset:32
	global_load_dwordx4 v[28:31], v2, s[30:31] offset:48
	s_waitcnt vmcnt(38)
	v_cvt_scalef32_pk32_f32_fp6 v[128:159], v[160:165], 1.0
	v_pk_mul_f32 v[116:117], v[128:129], v[80:81]
	v_pk_mul_f32 v[118:119], v[130:131], v[82:83]
	v_pk_mul_f32 v[120:121], v[132:133], v[84:85]
	v_pk_mul_f32 v[122:123], v[134:135], v[86:87]
	v_pk_fma_f32 v[116:117], v[136:137], v[88:89], v[116:117]
	v_pk_fma_f32 v[118:119], v[138:139], v[90:91], v[118:119]
	v_pk_fma_f32 v[120:121], v[140:141], v[92:93], v[120:121]
	v_pk_fma_f32 v[122:123], v[142:143], v[94:95], v[122:123]
	v_pk_fma_f32 v[116:117], v[144:145], v[96:97], v[116:117]
	v_pk_fma_f32 v[118:119], v[146:147], v[98:99], v[118:119]
	v_pk_fma_f32 v[120:121], v[148:149], v[100:101], v[120:121]
	v_pk_fma_f32 v[122:123], v[150:151], v[102:103], v[122:123]
	v_pk_fma_f32 v[116:117], v[152:153], v[104:105], v[116:117]
	v_pk_fma_f32 v[118:119], v[154:155], v[106:107], v[118:119]
	v_pk_fma_f32 v[120:121], v[156:157], v[108:109], v[120:121]
	v_pk_fma_f32 v[122:123], v[158:159], v[110:111], v[122:123]
	v_pk_add_f32 v[116:117], v[116:117], v[118:119]
	v_pk_add_f32 v[120:121], v[120:121], v[122:123]
	v_pk_add_f32 v[116:117], v[116:117], v[120:121]
	v_add_f32_e32 v126, v116, v117
	v_lshl_add_u32 v7, v32, 7, v1
	v_lshl_add_u32 v8, v32, 6, v125
	v_add_f32_dpp v126, v126, v126 quad_perm:[1,0,3,2] row_mask:0xf bank_mask:0xf
	global_load_dwordx4 v[160:163], v7, s[48:49] sc1
	s_nop 0
	v_add_f32_dpp v126, v126, v126 quad_perm:[2,3,0,1] row_mask:0xf bank_mask:0xf
	global_load_dwordx2 v[164:165], v8, s[48:49] sc1
	s_nop 0
	v_add_f32_dpp v126, v126, v126 row_half_mirror row_mask:0xf bank_mask:0xf
	v_cndmask_b32_e64 v12, v12, v126, s[60:61]
	s_waitcnt vmcnt(38)
	v_cvt_scalef32_pk32_f32_fp6 v[128:159], v[166:171], 1.0
	v_pk_mul_f32 v[116:117], v[128:129], v[80:81]
	v_pk_mul_f32 v[118:119], v[130:131], v[82:83]
	v_pk_mul_f32 v[120:121], v[132:133], v[84:85]
	v_pk_mul_f32 v[122:123], v[134:135], v[86:87]
	v_pk_fma_f32 v[116:117], v[136:137], v[88:89], v[116:117]
	v_pk_fma_f32 v[118:119], v[138:139], v[90:91], v[118:119]
	v_pk_fma_f32 v[120:121], v[140:141], v[92:93], v[120:121]
	v_pk_fma_f32 v[122:123], v[142:143], v[94:95], v[122:123]
	v_pk_fma_f32 v[116:117], v[144:145], v[96:97], v[116:117]
	v_pk_fma_f32 v[118:119], v[146:147], v[98:99], v[118:119]
	v_pk_fma_f32 v[120:121], v[148:149], v[100:101], v[120:121]
	v_pk_fma_f32 v[122:123], v[150:151], v[102:103], v[122:123]
	v_pk_fma_f32 v[116:117], v[152:153], v[104:105], v[116:117]
	v_pk_fma_f32 v[118:119], v[154:155], v[106:107], v[118:119]
	v_pk_fma_f32 v[120:121], v[156:157], v[108:109], v[120:121]
	v_pk_fma_f32 v[122:123], v[158:159], v[110:111], v[122:123]
	v_pk_add_f32 v[116:117], v[116:117], v[118:119]
	v_pk_add_f32 v[120:121], v[120:121], v[122:123]
	v_pk_add_f32 v[116:117], v[116:117], v[120:121]
	v_add_f32_e32 v126, v116, v117
	v_lshl_add_u32 v7, v33, 7, v1
	v_lshl_add_u32 v8, v33, 6, v125
	v_add_f32_dpp v126, v126, v126 quad_perm:[1,0,3,2] row_mask:0xf bank_mask:0xf
	global_load_dwordx4 v[166:169], v7, s[48:49] sc1
	s_nop 0
	v_add_f32_dpp v126, v126, v126 quad_perm:[2,3,0,1] row_mask:0xf bank_mask:0xf
	global_load_dwordx2 v[170:171], v8, s[48:49] sc1
	s_nop 0
	v_add_f32_dpp v126, v126, v126 row_half_mirror row_mask:0xf bank_mask:0xf
	v_cndmask_b32_e64 v12, v12, v126, s[62:63]
	s_waitcnt vmcnt(38)
	v_cvt_scalef32_pk32_f32_fp6 v[128:159], v[172:177], 1.0
	v_pk_mul_f32 v[116:117], v[128:129], v[80:81]
	v_pk_mul_f32 v[118:119], v[130:131], v[82:83]
	v_pk_mul_f32 v[120:121], v[132:133], v[84:85]
	v_pk_mul_f32 v[122:123], v[134:135], v[86:87]
	v_pk_fma_f32 v[116:117], v[136:137], v[88:89], v[116:117]
	v_pk_fma_f32 v[118:119], v[138:139], v[90:91], v[118:119]
	v_pk_fma_f32 v[120:121], v[140:141], v[92:93], v[120:121]
	v_pk_fma_f32 v[122:123], v[142:143], v[94:95], v[122:123]
	v_pk_fma_f32 v[116:117], v[144:145], v[96:97], v[116:117]
	v_pk_fma_f32 v[118:119], v[146:147], v[98:99], v[118:119]
	v_pk_fma_f32 v[120:121], v[148:149], v[100:101], v[120:121]
	v_pk_fma_f32 v[122:123], v[150:151], v[102:103], v[122:123]
	v_pk_fma_f32 v[116:117], v[152:153], v[104:105], v[116:117]
	v_pk_fma_f32 v[118:119], v[154:155], v[106:107], v[118:119]
	v_pk_fma_f32 v[120:121], v[156:157], v[108:109], v[120:121]
	v_pk_fma_f32 v[122:123], v[158:159], v[110:111], v[122:123]
	v_pk_add_f32 v[116:117], v[116:117], v[118:119]
	v_pk_add_f32 v[120:121], v[120:121], v[122:123]
	v_pk_add_f32 v[116:117], v[116:117], v[120:121]
	v_add_f32_e32 v126, v116, v117
	v_lshl_add_u32 v7, v34, 7, v1
	v_lshl_add_u32 v8, v34, 6, v125
	v_add_f32_dpp v126, v126, v126 quad_perm:[1,0,3,2] row_mask:0xf bank_mask:0xf
	global_load_dwordx4 v[172:175], v7, s[48:49] sc1
	s_nop 0
	v_add_f32_dpp v126, v126, v126 quad_perm:[2,3,0,1] row_mask:0xf bank_mask:0xf
	global_load_dwordx2 v[176:177], v8, s[48:49] sc1
	s_nop 0
	v_add_f32_dpp v126, v126, v126 row_half_mirror row_mask:0xf bank_mask:0xf
	v_cndmask_b32_e64 v12, v12, v126, s[64:65]
	s_waitcnt vmcnt(38)
	v_cvt_scalef32_pk32_f32_fp6 v[128:159], v[178:183], 1.0
	v_pk_mul_f32 v[116:117], v[128:129], v[80:81]
	v_pk_mul_f32 v[118:119], v[130:131], v[82:83]
	v_pk_mul_f32 v[120:121], v[132:133], v[84:85]
	v_pk_mul_f32 v[122:123], v[134:135], v[86:87]
	v_pk_fma_f32 v[116:117], v[136:137], v[88:89], v[116:117]
	v_pk_fma_f32 v[118:119], v[138:139], v[90:91], v[118:119]
	v_pk_fma_f32 v[120:121], v[140:141], v[92:93], v[120:121]
	v_pk_fma_f32 v[122:123], v[142:143], v[94:95], v[122:123]
	v_pk_fma_f32 v[116:117], v[144:145], v[96:97], v[116:117]
	v_pk_fma_f32 v[118:119], v[146:147], v[98:99], v[118:119]
	v_pk_fma_f32 v[120:121], v[148:149], v[100:101], v[120:121]
	v_pk_fma_f32 v[122:123], v[150:151], v[102:103], v[122:123]
	v_pk_fma_f32 v[116:117], v[152:153], v[104:105], v[116:117]
	v_pk_fma_f32 v[118:119], v[154:155], v[106:107], v[118:119]
	v_pk_fma_f32 v[120:121], v[156:157], v[108:109], v[120:121]
	v_pk_fma_f32 v[122:123], v[158:159], v[110:111], v[122:123]
	v_pk_add_f32 v[116:117], v[116:117], v[118:119]
	v_pk_add_f32 v[120:121], v[120:121], v[122:123]
	v_pk_add_f32 v[116:117], v[116:117], v[120:121]
	v_add_f32_e32 v126, v116, v117
	v_lshl_add_u32 v7, v35, 7, v1
	v_lshl_add_u32 v8, v35, 6, v125
	v_add_f32_dpp v126, v126, v126 quad_perm:[1,0,3,2] row_mask:0xf bank_mask:0xf
	global_load_dwordx4 v[178:181], v7, s[48:49] sc1
	s_nop 0
	v_add_f32_dpp v126, v126, v126 quad_perm:[2,3,0,1] row_mask:0xf bank_mask:0xf
	global_load_dwordx2 v[182:183], v8, s[48:49] sc1
	s_nop 0
	v_add_f32_dpp v126, v126, v126 row_half_mirror row_mask:0xf bank_mask:0xf
	v_cndmask_b32_e64 v12, v12, v126, s[66:67]
	s_waitcnt vmcnt(38)
	v_cvt_scalef32_pk32_f32_fp6 v[128:159], v[184:189], 1.0
	v_pk_mul_f32 v[116:117], v[128:129], v[80:81]
	v_pk_mul_f32 v[118:119], v[130:131], v[82:83]
	v_pk_mul_f32 v[120:121], v[132:133], v[84:85]
	v_pk_mul_f32 v[122:123], v[134:135], v[86:87]
	v_pk_fma_f32 v[116:117], v[136:137], v[88:89], v[116:117]
	v_pk_fma_f32 v[118:119], v[138:139], v[90:91], v[118:119]
	v_pk_fma_f32 v[120:121], v[140:141], v[92:93], v[120:121]
	v_pk_fma_f32 v[122:123], v[142:143], v[94:95], v[122:123]
	v_pk_fma_f32 v[116:117], v[144:145], v[96:97], v[116:117]
	v_pk_fma_f32 v[118:119], v[146:147], v[98:99], v[118:119]
	v_pk_fma_f32 v[120:121], v[148:149], v[100:101], v[120:121]
	v_pk_fma_f32 v[122:123], v[150:151], v[102:103], v[122:123]
	v_pk_fma_f32 v[116:117], v[152:153], v[104:105], v[116:117]
	v_pk_fma_f32 v[118:119], v[154:155], v[106:107], v[118:119]
	v_pk_fma_f32 v[120:121], v[156:157], v[108:109], v[120:121]
	v_pk_fma_f32 v[122:123], v[158:159], v[110:111], v[122:123]
	v_pk_add_f32 v[116:117], v[116:117], v[118:119]
	v_pk_add_f32 v[120:121], v[120:121], v[122:123]
	v_pk_add_f32 v[116:117], v[116:117], v[120:121]
	v_add_f32_e32 v126, v116, v117
	v_lshl_add_u32 v7, v36, 7, v1
	v_lshl_add_u32 v8, v36, 6, v125
	v_add_f32_dpp v126, v126, v126 quad_perm:[1,0,3,2] row_mask:0xf bank_mask:0xf
	global_load_dwordx4 v[184:187], v7, s[48:49] sc1
	s_nop 0
	v_add_f32_dpp v126, v126, v126 quad_perm:[2,3,0,1] row_mask:0xf bank_mask:0xf
	global_load_dwordx2 v[188:189], v8, s[48:49] sc1
	s_nop 0
	v_add_f32_dpp v126, v126, v126 row_half_mirror row_mask:0xf bank_mask:0xf
	v_cndmask_b32_e64 v12, v12, v126, s[68:69]
	s_waitcnt vmcnt(38)
	v_cvt_scalef32_pk32_f32_fp6 v[128:159], v[190:195], 1.0
	v_pk_mul_f32 v[116:117], v[128:129], v[80:81]
	v_pk_mul_f32 v[118:119], v[130:131], v[82:83]
	v_pk_mul_f32 v[120:121], v[132:133], v[84:85]
	v_pk_mul_f32 v[122:123], v[134:135], v[86:87]
	v_pk_fma_f32 v[116:117], v[136:137], v[88:89], v[116:117]
	v_pk_fma_f32 v[118:119], v[138:139], v[90:91], v[118:119]
	v_pk_fma_f32 v[120:121], v[140:141], v[92:93], v[120:121]
	v_pk_fma_f32 v[122:123], v[142:143], v[94:95], v[122:123]
	v_pk_fma_f32 v[116:117], v[144:145], v[96:97], v[116:117]
	v_pk_fma_f32 v[118:119], v[146:147], v[98:99], v[118:119]
	v_pk_fma_f32 v[120:121], v[148:149], v[100:101], v[120:121]
	v_pk_fma_f32 v[122:123], v[150:151], v[102:103], v[122:123]
	v_pk_fma_f32 v[116:117], v[152:153], v[104:105], v[116:117]
	v_pk_fma_f32 v[118:119], v[154:155], v[106:107], v[118:119]
	v_pk_fma_f32 v[120:121], v[156:157], v[108:109], v[120:121]
	v_pk_fma_f32 v[122:123], v[158:159], v[110:111], v[122:123]
	v_pk_add_f32 v[116:117], v[116:117], v[118:119]
	v_pk_add_f32 v[120:121], v[120:121], v[122:123]
	v_pk_add_f32 v[116:117], v[116:117], v[120:121]
	v_add_f32_e32 v126, v116, v117
	v_lshl_add_u32 v7, v37, 7, v1
	v_lshl_add_u32 v8, v37, 6, v125
	v_add_f32_dpp v126, v126, v126 quad_perm:[1,0,3,2] row_mask:0xf bank_mask:0xf
	global_load_dwordx4 v[190:193], v7, s[48:49] sc1
	s_nop 0
	v_add_f32_dpp v126, v126, v126 quad_perm:[2,3,0,1] row_mask:0xf bank_mask:0xf
	global_load_dwordx2 v[194:195], v8, s[48:49] sc1
	s_nop 0
	v_add_f32_dpp v126, v126, v126 row_half_mirror row_mask:0xf bank_mask:0xf
	v_cndmask_b32_e64 v12, v12, v126, s[70:71]
	s_waitcnt vmcnt(38)
	v_cvt_scalef32_pk32_f32_fp6 v[128:159], v[196:201], 1.0
	v_pk_mul_f32 v[116:117], v[128:129], v[80:81]
	v_pk_mul_f32 v[118:119], v[130:131], v[82:83]
	v_pk_mul_f32 v[120:121], v[132:133], v[84:85]
	v_pk_mul_f32 v[122:123], v[134:135], v[86:87]
	v_pk_fma_f32 v[116:117], v[136:137], v[88:89], v[116:117]
	v_pk_fma_f32 v[118:119], v[138:139], v[90:91], v[118:119]
	v_pk_fma_f32 v[120:121], v[140:141], v[92:93], v[120:121]
	v_pk_fma_f32 v[122:123], v[142:143], v[94:95], v[122:123]
	v_pk_fma_f32 v[116:117], v[144:145], v[96:97], v[116:117]
	v_pk_fma_f32 v[118:119], v[146:147], v[98:99], v[118:119]
	v_pk_fma_f32 v[120:121], v[148:149], v[100:101], v[120:121]
	v_pk_fma_f32 v[122:123], v[150:151], v[102:103], v[122:123]
	v_pk_fma_f32 v[116:117], v[152:153], v[104:105], v[116:117]
	v_pk_fma_f32 v[118:119], v[154:155], v[106:107], v[118:119]
	v_pk_fma_f32 v[120:121], v[156:157], v[108:109], v[120:121]
	v_pk_fma_f32 v[122:123], v[158:159], v[110:111], v[122:123]
	v_pk_add_f32 v[116:117], v[116:117], v[118:119]
	v_pk_add_f32 v[120:121], v[120:121], v[122:123]
	v_pk_add_f32 v[116:117], v[116:117], v[120:121]
	v_add_f32_e32 v126, v116, v117
	v_lshl_add_u32 v7, v38, 7, v1
	v_lshl_add_u32 v8, v38, 6, v125
	v_add_f32_dpp v126, v126, v126 quad_perm:[1,0,3,2] row_mask:0xf bank_mask:0xf
	global_load_dwordx4 v[196:199], v7, s[48:49] sc1
	s_nop 0
	v_add_f32_dpp v126, v126, v126 quad_perm:[2,3,0,1] row_mask:0xf bank_mask:0xf
	global_load_dwordx2 v[200:201], v8, s[48:49] sc1
	s_nop 0
	v_add_f32_dpp v126, v126, v126 row_half_mirror row_mask:0xf bank_mask:0xf
	v_cndmask_b32_e64 v12, v12, v126, s[72:73]
	s_waitcnt vmcnt(38)
	v_cvt_scalef32_pk32_f32_fp6 v[128:159], v[202:207], 1.0
	v_pk_mul_f32 v[116:117], v[128:129], v[80:81]
	v_pk_mul_f32 v[118:119], v[130:131], v[82:83]
	v_pk_mul_f32 v[120:121], v[132:133], v[84:85]
	v_pk_mul_f32 v[122:123], v[134:135], v[86:87]
	v_pk_fma_f32 v[116:117], v[136:137], v[88:89], v[116:117]
	v_pk_fma_f32 v[118:119], v[138:139], v[90:91], v[118:119]
	v_pk_fma_f32 v[120:121], v[140:141], v[92:93], v[120:121]
	v_pk_fma_f32 v[122:123], v[142:143], v[94:95], v[122:123]
	v_pk_fma_f32 v[116:117], v[144:145], v[96:97], v[116:117]
	v_pk_fma_f32 v[118:119], v[146:147], v[98:99], v[118:119]
	v_pk_fma_f32 v[120:121], v[148:149], v[100:101], v[120:121]
	v_pk_fma_f32 v[122:123], v[150:151], v[102:103], v[122:123]
	v_pk_fma_f32 v[116:117], v[152:153], v[104:105], v[116:117]
	v_pk_fma_f32 v[118:119], v[154:155], v[106:107], v[118:119]
	v_pk_fma_f32 v[120:121], v[156:157], v[108:109], v[120:121]
	v_pk_fma_f32 v[122:123], v[158:159], v[110:111], v[122:123]
	v_pk_add_f32 v[116:117], v[116:117], v[118:119]
	v_pk_add_f32 v[120:121], v[120:121], v[122:123]
	v_pk_add_f32 v[116:117], v[116:117], v[120:121]
	v_add_f32_e32 v126, v116, v117
	v_lshl_add_u32 v7, v39, 7, v1
	v_lshl_add_u32 v8, v39, 6, v125
	v_add_f32_dpp v126, v126, v126 quad_perm:[1,0,3,2] row_mask:0xf bank_mask:0xf
	global_load_dwordx4 v[202:205], v7, s[48:49] sc1
	s_nop 0
	v_add_f32_dpp v126, v126, v126 quad_perm:[2,3,0,1] row_mask:0xf bank_mask:0xf
	global_load_dwordx2 v[206:207], v8, s[48:49] sc1
	s_nop 0
	v_add_f32_dpp v126, v126, v126 row_half_mirror row_mask:0xf bank_mask:0xf
	v_cndmask_b32_e64 v12, v12, v126, s[74:75]
	s_waitcnt vmcnt(38)
	v_cvt_scalef32_pk32_f32_fp6 v[128:159], v[208:213], 1.0
	v_pk_mul_f32 v[116:117], v[128:129], v[80:81]
	v_pk_mul_f32 v[118:119], v[130:131], v[82:83]
	v_pk_mul_f32 v[120:121], v[132:133], v[84:85]
	v_pk_mul_f32 v[122:123], v[134:135], v[86:87]
	v_pk_fma_f32 v[116:117], v[136:137], v[88:89], v[116:117]
	v_pk_fma_f32 v[118:119], v[138:139], v[90:91], v[118:119]
	v_pk_fma_f32 v[120:121], v[140:141], v[92:93], v[120:121]
	v_pk_fma_f32 v[122:123], v[142:143], v[94:95], v[122:123]
	v_pk_fma_f32 v[116:117], v[144:145], v[96:97], v[116:117]
	v_pk_fma_f32 v[118:119], v[146:147], v[98:99], v[118:119]
	v_pk_fma_f32 v[120:121], v[148:149], v[100:101], v[120:121]
	v_pk_fma_f32 v[122:123], v[150:151], v[102:103], v[122:123]
	v_pk_fma_f32 v[116:117], v[152:153], v[104:105], v[116:117]
	v_pk_fma_f32 v[118:119], v[154:155], v[106:107], v[118:119]
	v_pk_fma_f32 v[120:121], v[156:157], v[108:109], v[120:121]
	v_pk_fma_f32 v[122:123], v[158:159], v[110:111], v[122:123]
	v_pk_add_f32 v[116:117], v[116:117], v[118:119]
	v_pk_add_f32 v[120:121], v[120:121], v[122:123]
	v_pk_add_f32 v[116:117], v[116:117], v[120:121]
	v_add_f32_e32 v126, v116, v117
	v_lshl_add_u32 v7, v40, 7, v1
	v_lshl_add_u32 v8, v40, 6, v125
	v_add_f32_dpp v126, v126, v126 quad_perm:[1,0,3,2] row_mask:0xf bank_mask:0xf
	global_load_dwordx4 v[208:211], v7, s[48:49] sc1
	s_nop 0
	v_add_f32_dpp v126, v126, v126 quad_perm:[2,3,0,1] row_mask:0xf bank_mask:0xf
	global_load_dwordx2 v[212:213], v8, s[48:49] sc1
	s_nop 0
	v_add_f32_dpp v126, v126, v126 row_half_mirror row_mask:0xf bank_mask:0xf
	v_cndmask_b32_e64 v15, v15, v126, s[60:61]
	s_waitcnt vmcnt(38)
	v_cvt_scalef32_pk32_f32_fp6 v[128:159], v[214:219], 1.0
	v_pk_mul_f32 v[116:117], v[128:129], v[80:81]
	v_pk_mul_f32 v[118:119], v[130:131], v[82:83]
	v_pk_mul_f32 v[120:121], v[132:133], v[84:85]
	v_pk_mul_f32 v[122:123], v[134:135], v[86:87]
	v_pk_fma_f32 v[116:117], v[136:137], v[88:89], v[116:117]
	v_pk_fma_f32 v[118:119], v[138:139], v[90:91], v[118:119]
	v_pk_fma_f32 v[120:121], v[140:141], v[92:93], v[120:121]
	v_pk_fma_f32 v[122:123], v[142:143], v[94:95], v[122:123]
	v_pk_fma_f32 v[116:117], v[144:145], v[96:97], v[116:117]
	v_pk_fma_f32 v[118:119], v[146:147], v[98:99], v[118:119]
	v_pk_fma_f32 v[120:121], v[148:149], v[100:101], v[120:121]
	v_pk_fma_f32 v[122:123], v[150:151], v[102:103], v[122:123]
	v_pk_fma_f32 v[116:117], v[152:153], v[104:105], v[116:117]
	v_pk_fma_f32 v[118:119], v[154:155], v[106:107], v[118:119]
	v_pk_fma_f32 v[120:121], v[156:157], v[108:109], v[120:121]
	v_pk_fma_f32 v[122:123], v[158:159], v[110:111], v[122:123]
	v_pk_add_f32 v[116:117], v[116:117], v[118:119]
	v_pk_add_f32 v[120:121], v[120:121], v[122:123]
	v_pk_add_f32 v[116:117], v[116:117], v[120:121]
	v_add_f32_e32 v126, v116, v117
	v_lshl_add_u32 v7, v41, 7, v1
	v_lshl_add_u32 v8, v41, 6, v125
	v_add_f32_dpp v126, v126, v126 quad_perm:[1,0,3,2] row_mask:0xf bank_mask:0xf
	global_load_dwordx4 v[214:217], v7, s[48:49] sc1
	s_nop 0
	v_add_f32_dpp v126, v126, v126 quad_perm:[2,3,0,1] row_mask:0xf bank_mask:0xf
	global_load_dwordx2 v[218:219], v8, s[48:49] sc1
	s_nop 0
	v_add_f32_dpp v126, v126, v126 row_half_mirror row_mask:0xf bank_mask:0xf
	v_cndmask_b32_e64 v15, v15, v126, s[62:63]
	s_waitcnt vmcnt(38)
	v_cvt_scalef32_pk32_f32_fp6 v[128:159], v[220:225], 1.0
	v_pk_mul_f32 v[116:117], v[128:129], v[80:81]
	v_pk_mul_f32 v[118:119], v[130:131], v[82:83]
	v_pk_mul_f32 v[120:121], v[132:133], v[84:85]
	v_pk_mul_f32 v[122:123], v[134:135], v[86:87]
	v_pk_fma_f32 v[116:117], v[136:137], v[88:89], v[116:117]
	v_pk_fma_f32 v[118:119], v[138:139], v[90:91], v[118:119]
	v_pk_fma_f32 v[120:121], v[140:141], v[92:93], v[120:121]
	v_pk_fma_f32 v[122:123], v[142:143], v[94:95], v[122:123]
	v_pk_fma_f32 v[116:117], v[144:145], v[96:97], v[116:117]
	v_pk_fma_f32 v[118:119], v[146:147], v[98:99], v[118:119]
	v_pk_fma_f32 v[120:121], v[148:149], v[100:101], v[120:121]
	v_pk_fma_f32 v[122:123], v[150:151], v[102:103], v[122:123]
	v_pk_fma_f32 v[116:117], v[152:153], v[104:105], v[116:117]
	v_pk_fma_f32 v[118:119], v[154:155], v[106:107], v[118:119]
	v_pk_fma_f32 v[120:121], v[156:157], v[108:109], v[120:121]
	v_pk_fma_f32 v[122:123], v[158:159], v[110:111], v[122:123]
	v_pk_add_f32 v[116:117], v[116:117], v[118:119]
	v_pk_add_f32 v[120:121], v[120:121], v[122:123]
	v_pk_add_f32 v[116:117], v[116:117], v[120:121]
	v_add_f32_e32 v126, v116, v117
	v_lshl_add_u32 v7, v42, 7, v1
	v_lshl_add_u32 v8, v42, 6, v125
	v_add_f32_dpp v126, v126, v126 quad_perm:[1,0,3,2] row_mask:0xf bank_mask:0xf
	global_load_dwordx4 v[220:223], v7, s[48:49] sc1
	s_nop 0
	v_add_f32_dpp v126, v126, v126 quad_perm:[2,3,0,1] row_mask:0xf bank_mask:0xf
	global_load_dwordx2 v[224:225], v8, s[48:49] sc1
	s_nop 0
	v_add_f32_dpp v126, v126, v126 row_half_mirror row_mask:0xf bank_mask:0xf
	v_cndmask_b32_e64 v15, v15, v126, s[64:65]
	s_waitcnt vmcnt(38)
	v_cvt_scalef32_pk32_f32_fp6 v[128:159], v[226:231], 1.0
	v_pk_mul_f32 v[116:117], v[128:129], v[80:81]
	v_pk_mul_f32 v[118:119], v[130:131], v[82:83]
	v_pk_mul_f32 v[120:121], v[132:133], v[84:85]
	v_pk_mul_f32 v[122:123], v[134:135], v[86:87]
	v_pk_fma_f32 v[116:117], v[136:137], v[88:89], v[116:117]
	v_pk_fma_f32 v[118:119], v[138:139], v[90:91], v[118:119]
	v_pk_fma_f32 v[120:121], v[140:141], v[92:93], v[120:121]
	v_pk_fma_f32 v[122:123], v[142:143], v[94:95], v[122:123]
	v_pk_fma_f32 v[116:117], v[144:145], v[96:97], v[116:117]
	v_pk_fma_f32 v[118:119], v[146:147], v[98:99], v[118:119]
	v_pk_fma_f32 v[120:121], v[148:149], v[100:101], v[120:121]
	v_pk_fma_f32 v[122:123], v[150:151], v[102:103], v[122:123]
	v_pk_fma_f32 v[116:117], v[152:153], v[104:105], v[116:117]
	v_pk_fma_f32 v[118:119], v[154:155], v[106:107], v[118:119]
	v_pk_fma_f32 v[120:121], v[156:157], v[108:109], v[120:121]
	v_pk_fma_f32 v[122:123], v[158:159], v[110:111], v[122:123]
	v_pk_add_f32 v[116:117], v[116:117], v[118:119]
	v_pk_add_f32 v[120:121], v[120:121], v[122:123]
	v_pk_add_f32 v[116:117], v[116:117], v[120:121]
	v_add_f32_e32 v126, v116, v117
	v_lshl_add_u32 v7, v43, 7, v1
	v_lshl_add_u32 v8, v43, 6, v125
	v_add_f32_dpp v126, v126, v126 quad_perm:[1,0,3,2] row_mask:0xf bank_mask:0xf
	global_load_dwordx4 v[226:229], v7, s[48:49] sc1
	s_nop 0
	v_add_f32_dpp v126, v126, v126 quad_perm:[2,3,0,1] row_mask:0xf bank_mask:0xf
	global_load_dwordx2 v[230:231], v8, s[48:49] sc1
	s_nop 0
	v_add_f32_dpp v126, v126, v126 row_half_mirror row_mask:0xf bank_mask:0xf
	v_cndmask_b32_e64 v15, v15, v126, s[66:67]
	s_waitcnt vmcnt(38)
	v_cvt_scalef32_pk32_f32_fp6 v[128:159], v[232:237], 1.0
	v_pk_mul_f32 v[116:117], v[128:129], v[80:81]
	v_pk_mul_f32 v[118:119], v[130:131], v[82:83]
	v_pk_mul_f32 v[120:121], v[132:133], v[84:85]
	v_pk_mul_f32 v[122:123], v[134:135], v[86:87]
	v_pk_fma_f32 v[116:117], v[136:137], v[88:89], v[116:117]
	v_pk_fma_f32 v[118:119], v[138:139], v[90:91], v[118:119]
	v_pk_fma_f32 v[120:121], v[140:141], v[92:93], v[120:121]
	v_pk_fma_f32 v[122:123], v[142:143], v[94:95], v[122:123]
	v_pk_fma_f32 v[116:117], v[144:145], v[96:97], v[116:117]
	v_pk_fma_f32 v[118:119], v[146:147], v[98:99], v[118:119]
	v_pk_fma_f32 v[120:121], v[148:149], v[100:101], v[120:121]
	v_pk_fma_f32 v[122:123], v[150:151], v[102:103], v[122:123]
	v_pk_fma_f32 v[116:117], v[152:153], v[104:105], v[116:117]
	v_pk_fma_f32 v[118:119], v[154:155], v[106:107], v[118:119]
	v_pk_fma_f32 v[120:121], v[156:157], v[108:109], v[120:121]
	v_pk_fma_f32 v[122:123], v[158:159], v[110:111], v[122:123]
	v_pk_add_f32 v[116:117], v[116:117], v[118:119]
	v_pk_add_f32 v[120:121], v[120:121], v[122:123]
	v_pk_add_f32 v[116:117], v[116:117], v[120:121]
	v_add_f32_e32 v126, v116, v117
	v_lshl_add_u32 v7, v44, 7, v1
	v_lshl_add_u32 v8, v44, 6, v125
	v_add_f32_dpp v126, v126, v126 quad_perm:[1,0,3,2] row_mask:0xf bank_mask:0xf
	global_load_dwordx4 v[232:235], v7, s[48:49] sc1
	s_nop 0
	v_add_f32_dpp v126, v126, v126 quad_perm:[2,3,0,1] row_mask:0xf bank_mask:0xf
	global_load_dwordx2 v[236:237], v8, s[48:49] sc1
	s_nop 0
	v_add_f32_dpp v126, v126, v126 row_half_mirror row_mask:0xf bank_mask:0xf
	v_cndmask_b32_e64 v15, v15, v126, s[68:69]
	s_waitcnt vmcnt(38)
	v_cvt_scalef32_pk32_f32_fp6 v[128:159], v[238:243], 1.0
	v_pk_mul_f32 v[116:117], v[128:129], v[80:81]
	v_pk_mul_f32 v[118:119], v[130:131], v[82:83]
	v_pk_mul_f32 v[120:121], v[132:133], v[84:85]
	v_pk_mul_f32 v[122:123], v[134:135], v[86:87]
	v_pk_fma_f32 v[116:117], v[136:137], v[88:89], v[116:117]
	v_pk_fma_f32 v[118:119], v[138:139], v[90:91], v[118:119]
	v_pk_fma_f32 v[120:121], v[140:141], v[92:93], v[120:121]
	v_pk_fma_f32 v[122:123], v[142:143], v[94:95], v[122:123]
	v_pk_fma_f32 v[116:117], v[144:145], v[96:97], v[116:117]
	v_pk_fma_f32 v[118:119], v[146:147], v[98:99], v[118:119]
	v_pk_fma_f32 v[120:121], v[148:149], v[100:101], v[120:121]
	v_pk_fma_f32 v[122:123], v[150:151], v[102:103], v[122:123]
	v_pk_fma_f32 v[116:117], v[152:153], v[104:105], v[116:117]
	v_pk_fma_f32 v[118:119], v[154:155], v[106:107], v[118:119]
	v_pk_fma_f32 v[120:121], v[156:157], v[108:109], v[120:121]
	v_pk_fma_f32 v[122:123], v[158:159], v[110:111], v[122:123]
	v_pk_add_f32 v[116:117], v[116:117], v[118:119]
	v_pk_add_f32 v[120:121], v[120:121], v[122:123]
	v_pk_add_f32 v[116:117], v[116:117], v[120:121]
	v_add_f32_e32 v126, v116, v117
	v_lshl_add_u32 v7, v45, 7, v1
	v_lshl_add_u32 v8, v45, 6, v125
	v_add_f32_dpp v126, v126, v126 quad_perm:[1,0,3,2] row_mask:0xf bank_mask:0xf
	global_load_dwordx4 v[238:241], v7, s[48:49] sc1
	s_nop 0
	v_add_f32_dpp v126, v126, v126 quad_perm:[2,3,0,1] row_mask:0xf bank_mask:0xf
	global_load_dwordx2 v[242:243], v8, s[48:49] sc1
	s_nop 0
	v_add_f32_dpp v126, v126, v126 row_half_mirror row_mask:0xf bank_mask:0xf
	v_cndmask_b32_e64 v15, v15, v126, s[70:71]
	s_waitcnt vmcnt(38)
	v_cvt_scalef32_pk32_f32_fp6 v[128:159], v[244:249], 1.0
	v_pk_mul_f32 v[116:117], v[128:129], v[80:81]
	v_pk_mul_f32 v[118:119], v[130:131], v[82:83]
	v_pk_mul_f32 v[120:121], v[132:133], v[84:85]
	v_pk_mul_f32 v[122:123], v[134:135], v[86:87]
	v_pk_fma_f32 v[116:117], v[136:137], v[88:89], v[116:117]
	v_pk_fma_f32 v[118:119], v[138:139], v[90:91], v[118:119]
	v_pk_fma_f32 v[120:121], v[140:141], v[92:93], v[120:121]
	v_pk_fma_f32 v[122:123], v[142:143], v[94:95], v[122:123]
	v_pk_fma_f32 v[116:117], v[144:145], v[96:97], v[116:117]
	v_pk_fma_f32 v[118:119], v[146:147], v[98:99], v[118:119]
	v_pk_fma_f32 v[120:121], v[148:149], v[100:101], v[120:121]
	v_pk_fma_f32 v[122:123], v[150:151], v[102:103], v[122:123]
	v_pk_fma_f32 v[116:117], v[152:153], v[104:105], v[116:117]
	v_pk_fma_f32 v[118:119], v[154:155], v[106:107], v[118:119]
	v_pk_fma_f32 v[120:121], v[156:157], v[108:109], v[120:121]
	v_pk_fma_f32 v[122:123], v[158:159], v[110:111], v[122:123]
	v_pk_add_f32 v[116:117], v[116:117], v[118:119]
	v_pk_add_f32 v[120:121], v[120:121], v[122:123]
	v_pk_add_f32 v[116:117], v[116:117], v[120:121]
	v_add_f32_e32 v126, v116, v117
	v_lshl_add_u32 v7, v46, 7, v1
	v_lshl_add_u32 v8, v46, 6, v125
	v_add_f32_dpp v126, v126, v126 quad_perm:[1,0,3,2] row_mask:0xf bank_mask:0xf
	global_load_dwordx4 v[244:247], v7, s[48:49] sc1
	s_nop 0
	v_add_f32_dpp v126, v126, v126 quad_perm:[2,3,0,1] row_mask:0xf bank_mask:0xf
	global_load_dwordx2 v[248:249], v8, s[48:49] sc1
	s_nop 0
	v_add_f32_dpp v126, v126, v126 row_half_mirror row_mask:0xf bank_mask:0xf
	v_cndmask_b32_e64 v15, v15, v126, s[72:73]
	s_waitcnt vmcnt(38)
	v_cvt_scalef32_pk32_f32_fp6 v[128:159], v[250:255], 1.0
	v_pk_mul_f32 v[116:117], v[128:129], v[80:81]
	v_pk_mul_f32 v[118:119], v[130:131], v[82:83]
	v_pk_mul_f32 v[120:121], v[132:133], v[84:85]
	v_pk_mul_f32 v[122:123], v[134:135], v[86:87]
	v_pk_fma_f32 v[116:117], v[136:137], v[88:89], v[116:117]
	v_pk_fma_f32 v[118:119], v[138:139], v[90:91], v[118:119]
	v_pk_fma_f32 v[120:121], v[140:141], v[92:93], v[120:121]
	v_pk_fma_f32 v[122:123], v[142:143], v[94:95], v[122:123]
	v_pk_fma_f32 v[116:117], v[144:145], v[96:97], v[116:117]
	v_pk_fma_f32 v[118:119], v[146:147], v[98:99], v[118:119]
	v_pk_fma_f32 v[120:121], v[148:149], v[100:101], v[120:121]
	v_pk_fma_f32 v[122:123], v[150:151], v[102:103], v[122:123]
	v_pk_fma_f32 v[116:117], v[152:153], v[104:105], v[116:117]
	v_pk_fma_f32 v[118:119], v[154:155], v[106:107], v[118:119]
	v_pk_fma_f32 v[120:121], v[156:157], v[108:109], v[120:121]
	v_pk_fma_f32 v[122:123], v[158:159], v[110:111], v[122:123]
	v_pk_add_f32 v[116:117], v[116:117], v[118:119]
	v_pk_add_f32 v[120:121], v[120:121], v[122:123]
	v_pk_add_f32 v[116:117], v[116:117], v[120:121]
	v_add_f32_e32 v126, v116, v117
	v_lshl_add_u32 v7, v47, 7, v1
	v_lshl_add_u32 v8, v47, 6, v125
	v_add_f32_dpp v126, v126, v126 quad_perm:[1,0,3,2] row_mask:0xf bank_mask:0xf
	global_load_dwordx4 v[250:253], v7, s[48:49] sc1
	s_nop 0
	v_add_f32_dpp v126, v126, v126 quad_perm:[2,3,0,1] row_mask:0xf bank_mask:0xf
	global_load_dwordx2 v[254:255], v8, s[48:49] sc1
	s_nop 0
	v_add_f32_dpp v126, v126, v126 row_half_mirror row_mask:0xf bank_mask:0xf
	v_cndmask_b32_e64 v15, v15, v126, s[74:75]
	v_mul_f32_e32 v12, v12, v127
	v_mul_f32_e32 v15, v15, v127
	global_store_dword v9, v12, s[44:45]
	global_store_dword v9, v15, s[44:45] offset:32
	s_add_u32 s28, s28, 1
	s_waitcnt vmcnt(34)
	ds_write_b128 v13, v[48:51]
	ds_read_b128 v[128:131], v124 offset:0
	ds_read_b128 v[132:135], v124 offset:16
	ds_read_b128 v[136:139], v124 offset:32
	ds_read_b128 v[140:143], v124 offset:48
	ds_read_b128 v[144:147], v124 offset:64
	ds_read_b128 v[148:151], v124 offset:80
	ds_read_b128 v[152:155], v124 offset:96
	ds_read_b128 v[156:159], v124 offset:112
	ds_read_b128 v[48:51], v14 offset:0
	ds_read_b128 v[52:55], v14 offset:16
	ds_read_b128 v[56:59], v14 offset:32
	ds_read_b128 v[60:63], v14 offset:48
	ds_read_b128 v[64:67], v14 offset:64
	ds_read_b128 v[68:71], v14 offset:80
	ds_read_b128 v[72:75], v14 offset:96
	ds_read_b128 v[76:79], v14 offset:112
	v_add_f32_e32 v126, v112, v113
	v_add_f32_e32 v127, v114, v115
	v_add_f32_e32 v126, v126, v127
	s_nop 1
	v_add_f32_dpp v126, v126, v126 quad_perm:[1,0,3,2] row_mask:0xf bank_mask:0xf
	s_nop 1
	v_add_f32_dpp v126, v126, v126 quad_perm:[2,3,0,1] row_mask:0xf bank_mask:0xf
	s_nop 1
	v_add_f32_dpp v126, v126, v126 row_half_mirror row_mask:0xf bank_mask:0xf
	s_nop 1
	v_mov_b32_e32 v127, 0x358637bd
	v_fmac_f32_e32 v127, 0x3a000000, v126
	v_rsq_f32_e32 v127, v127
	s_waitcnt lgkmcnt(0)
	v_pk_mul_f32 v[80:81], v[48:49], v[128:129]
	v_pk_mul_f32 v[82:83], v[50:51], v[130:131]
	v_pk_mul_f32 v[84:85], v[52:53], v[132:133]
	v_pk_mul_f32 v[86:87], v[54:55], v[134:135]
	v_pk_mul_f32 v[88:89], v[56:57], v[136:137]
	v_pk_mul_f32 v[90:91], v[58:59], v[138:139]
	v_pk_mul_f32 v[92:93], v[60:61], v[140:141]
	v_pk_mul_f32 v[94:95], v[62:63], v[142:143]
	v_pk_mul_f32 v[96:97], v[64:65], v[144:145]
	v_pk_mul_f32 v[98:99], v[66:67], v[146:147]
	v_pk_mul_f32 v[100:101], v[68:69], v[148:149]
	v_pk_mul_f32 v[102:103], v[70:71], v[150:151]
	v_pk_mul_f32 v[104:105], v[72:73], v[152:153]
	v_pk_mul_f32 v[106:107], v[74:75], v[154:155]
	v_pk_mul_f32 v[108:109], v[76:77], v[156:157]
	v_pk_mul_f32 v[110:111], v[78:79], v[158:159]
	s_add_u32 s40, s28, 0
	s_min_u32 s40, s40, 127
	s_lshl_b32 s40, s40, 8
	s_add_u32 s40, s40, s24
	s_lshl_b32 s29, s40, 12
	s_add_u32 s44, s50, s29
	s_addc_u32 s45, s51, 0
	s_add_u32 s40, s28, 1
	s_min_u32 s40, s40, 127
	s_lshl_b32 s40, s40, 8
	s_add_u32 s40, s40, s24
	s_lshl_b32 s29, s40, 13
	s_add_u32 s34, s10, s29
	s_addc_u32 s35, s11, 0
	global_load_dwordx4 v[48:51], v6, s[34:35]
	s_lshl_b32 s29, s40, 7
	s_add_u32 s38, s54, s29
	s_addc_u32 s39, s55, 0
	global_load_dwordx4 v[112:115], v1, s[38:39]
	s_add_u32 s40, s28, 2
	s_min_u32 s40, s40, 127
	s_lshl_b32 s40, s40, 8
	s_add_u32 s40, s40, s24
	s_lshl_b32 s29, s40, 9
	s_add_u32 s30, s4, s29
	s_addc_u32 s31, s5, 0
	global_load_dwordx4 v[32:35], v2, s[30:31] offset:0
	global_load_dwordx4 v[36:39], v2, s[30:31] offset:16
	global_load_dwordx4 v[40:43], v2, s[30:31] offset:32
	global_load_dwordx4 v[44:47], v2, s[30:31] offset:48
	s_waitcnt vmcnt(38)
	v_cvt_scalef32_pk32_f32_fp6 v[128:159], v[160:165], 1.0
	v_pk_mul_f32 v[116:117], v[128:129], v[80:81]
	v_pk_mul_f32 v[118:119], v[130:131], v[82:83]
	v_pk_mul_f32 v[120:121], v[132:133], v[84:85]
	v_pk_mul_f32 v[122:123], v[134:135], v[86:87]
	v_pk_fma_f32 v[116:117], v[136:137], v[88:89], v[116:117]
	v_pk_fma_f32 v[118:119], v[138:139], v[90:91], v[118:119]
	v_pk_fma_f32 v[120:121], v[140:141], v[92:93], v[120:121]
	v_pk_fma_f32 v[122:123], v[142:143], v[94:95], v[122:123]
	v_pk_fma_f32 v[116:117], v[144:145], v[96:97], v[116:117]
	v_pk_fma_f32 v[118:119], v[146:147], v[98:99], v[118:119]
	v_pk_fma_f32 v[120:121], v[148:149], v[100:101], v[120:121]
	v_pk_fma_f32 v[122:123], v[150:151], v[102:103], v[122:123]
	v_pk_fma_f32 v[116:117], v[152:153], v[104:105], v[116:117]
	v_pk_fma_f32 v[118:119], v[154:155], v[106:107], v[118:119]
	v_pk_fma_f32 v[120:121], v[156:157], v[108:109], v[120:121]
	v_pk_fma_f32 v[122:123], v[158:159], v[110:111], v[122:123]
	v_pk_add_f32 v[116:117], v[116:117], v[118:119]
	v_pk_add_f32 v[120:121], v[120:121], v[122:123]
	v_pk_add_f32 v[116:117], v[116:117], v[120:121]
	v_add_f32_e32 v126, v116, v117
	v_lshl_add_u32 v7, v16, 7, v1
	v_lshl_add_u32 v8, v16, 6, v125
	v_add_f32_dpp v126, v126, v126 quad_perm:[1,0,3,2] row_mask:0xf bank_mask:0xf
	global_load_dwordx4 v[160:163], v7, s[48:49] sc1
	s_nop 0
	v_add_f32_dpp v126, v126, v126 quad_perm:[2,3,0,1] row_mask:0xf bank_mask:0xf
	global_load_dwordx2 v[164:165], v8, s[48:49] sc1
	s_nop 0
	v_add_f32_dpp v126, v126, v126 row_half_mirror row_mask:0xf bank_mask:0xf
	v_cndmask_b32_e64 v12, v12, v126, s[60:61]
	s_waitcnt vmcnt(38)
	v_cvt_scalef32_pk32_f32_fp6 v[128:159], v[166:171], 1.0
	v_pk_mul_f32 v[116:117], v[128:129], v[80:81]
	v_pk_mul_f32 v[118:119], v[130:131], v[82:83]
	v_pk_mul_f32 v[120:121], v[132:133], v[84:85]
	v_pk_mul_f32 v[122:123], v[134:135], v[86:87]
	v_pk_fma_f32 v[116:117], v[136:137], v[88:89], v[116:117]
	v_pk_fma_f32 v[118:119], v[138:139], v[90:91], v[118:119]
	v_pk_fma_f32 v[120:121], v[140:141], v[92:93], v[120:121]
	v_pk_fma_f32 v[122:123], v[142:143], v[94:95], v[122:123]
	v_pk_fma_f32 v[116:117], v[144:145], v[96:97], v[116:117]
	v_pk_fma_f32 v[118:119], v[146:147], v[98:99], v[118:119]
	v_pk_fma_f32 v[120:121], v[148:149], v[100:101], v[120:121]
	v_pk_fma_f32 v[122:123], v[150:151], v[102:103], v[122:123]
	v_pk_fma_f32 v[116:117], v[152:153], v[104:105], v[116:117]
	v_pk_fma_f32 v[118:119], v[154:155], v[106:107], v[118:119]
	v_pk_fma_f32 v[120:121], v[156:157], v[108:109], v[120:121]
	v_pk_fma_f32 v[122:123], v[158:159], v[110:111], v[122:123]
	v_pk_add_f32 v[116:117], v[116:117], v[118:119]
	v_pk_add_f32 v[120:121], v[120:121], v[122:123]
	v_pk_add_f32 v[116:117], v[116:117], v[120:121]
	v_add_f32_e32 v126, v116, v117
	v_lshl_add_u32 v7, v17, 7, v1
	v_lshl_add_u32 v8, v17, 6, v125
	v_add_f32_dpp v126, v126, v126 quad_perm:[1,0,3,2] row_mask:0xf bank_mask:0xf
	global_load_dwordx4 v[166:169], v7, s[48:49] sc1
	s_nop 0
	v_add_f32_dpp v126, v126, v126 quad_perm:[2,3,0,1] row_mask:0xf bank_mask:0xf
	global_load_dwordx2 v[170:171], v8, s[48:49] sc1
	s_nop 0
	v_add_f32_dpp v126, v126, v126 row_half_mirror row_mask:0xf bank_mask:0xf
	v_cndmask_b32_e64 v12, v12, v126, s[62:63]
	s_waitcnt vmcnt(38)
	v_cvt_scalef32_pk32_f32_fp6 v[128:159], v[172:177], 1.0
	v_pk_mul_f32 v[116:117], v[128:129], v[80:81]
	v_pk_mul_f32 v[118:119], v[130:131], v[82:83]
	v_pk_mul_f32 v[120:121], v[132:133], v[84:85]
	v_pk_mul_f32 v[122:123], v[134:135], v[86:87]
	v_pk_fma_f32 v[116:117], v[136:137], v[88:89], v[116:117]
	v_pk_fma_f32 v[118:119], v[138:139], v[90:91], v[118:119]
	v_pk_fma_f32 v[120:121], v[140:141], v[92:93], v[120:121]
	v_pk_fma_f32 v[122:123], v[142:143], v[94:95], v[122:123]
	v_pk_fma_f32 v[116:117], v[144:145], v[96:97], v[116:117]
	v_pk_fma_f32 v[118:119], v[146:147], v[98:99], v[118:119]
	v_pk_fma_f32 v[120:121], v[148:149], v[100:101], v[120:121]
	v_pk_fma_f32 v[122:123], v[150:151], v[102:103], v[122:123]
	v_pk_fma_f32 v[116:117], v[152:153], v[104:105], v[116:117]
	v_pk_fma_f32 v[118:119], v[154:155], v[106:107], v[118:119]
	v_pk_fma_f32 v[120:121], v[156:157], v[108:109], v[120:121]
	v_pk_fma_f32 v[122:123], v[158:159], v[110:111], v[122:123]
	v_pk_add_f32 v[116:117], v[116:117], v[118:119]
	v_pk_add_f32 v[120:121], v[120:121], v[122:123]
	v_pk_add_f32 v[116:117], v[116:117], v[120:121]
	v_add_f32_e32 v126, v116, v117
	v_lshl_add_u32 v7, v18, 7, v1
	v_lshl_add_u32 v8, v18, 6, v125
	v_add_f32_dpp v126, v126, v126 quad_perm:[1,0,3,2] row_mask:0xf bank_mask:0xf
	global_load_dwordx4 v[172:175], v7, s[48:49] sc1
	s_nop 0
	v_add_f32_dpp v126, v126, v126 quad_perm:[2,3,0,1] row_mask:0xf bank_mask:0xf
	global_load_dwordx2 v[176:177], v8, s[48:49] sc1
	s_nop 0
	v_add_f32_dpp v126, v126, v126 row_half_mirror row_mask:0xf bank_mask:0xf
	v_cndmask_b32_e64 v12, v12, v126, s[64:65]
	s_waitcnt vmcnt(38)
	v_cvt_scalef32_pk32_f32_fp6 v[128:159], v[178:183], 1.0
	v_pk_mul_f32 v[116:117], v[128:129], v[80:81]
	v_pk_mul_f32 v[118:119], v[130:131], v[82:83]
	v_pk_mul_f32 v[120:121], v[132:133], v[84:85]
	v_pk_mul_f32 v[122:123], v[134:135], v[86:87]
	v_pk_fma_f32 v[116:117], v[136:137], v[88:89], v[116:117]
	v_pk_fma_f32 v[118:119], v[138:139], v[90:91], v[118:119]
	v_pk_fma_f32 v[120:121], v[140:141], v[92:93], v[120:121]
	v_pk_fma_f32 v[122:123], v[142:143], v[94:95], v[122:123]
	v_pk_fma_f32 v[116:117], v[144:145], v[96:97], v[116:117]
	v_pk_fma_f32 v[118:119], v[146:147], v[98:99], v[118:119]
	v_pk_fma_f32 v[120:121], v[148:149], v[100:101], v[120:121]
	v_pk_fma_f32 v[122:123], v[150:151], v[102:103], v[122:123]
	v_pk_fma_f32 v[116:117], v[152:153], v[104:105], v[116:117]
	v_pk_fma_f32 v[118:119], v[154:155], v[106:107], v[118:119]
	v_pk_fma_f32 v[120:121], v[156:157], v[108:109], v[120:121]
	v_pk_fma_f32 v[122:123], v[158:159], v[110:111], v[122:123]
	v_pk_add_f32 v[116:117], v[116:117], v[118:119]
	v_pk_add_f32 v[120:121], v[120:121], v[122:123]
	v_pk_add_f32 v[116:117], v[116:117], v[120:121]
	v_add_f32_e32 v126, v116, v117
	v_lshl_add_u32 v7, v19, 7, v1
	v_lshl_add_u32 v8, v19, 6, v125
	v_add_f32_dpp v126, v126, v126 quad_perm:[1,0,3,2] row_mask:0xf bank_mask:0xf
	global_load_dwordx4 v[178:181], v7, s[48:49] sc1
	s_nop 0
	v_add_f32_dpp v126, v126, v126 quad_perm:[2,3,0,1] row_mask:0xf bank_mask:0xf
	global_load_dwordx2 v[182:183], v8, s[48:49] sc1
	s_nop 0
	v_add_f32_dpp v126, v126, v126 row_half_mirror row_mask:0xf bank_mask:0xf
	v_cndmask_b32_e64 v12, v12, v126, s[66:67]
	s_waitcnt vmcnt(38)
	v_cvt_scalef32_pk32_f32_fp6 v[128:159], v[184:189], 1.0
	v_pk_mul_f32 v[116:117], v[128:129], v[80:81]
	v_pk_mul_f32 v[118:119], v[130:131], v[82:83]
	v_pk_mul_f32 v[120:121], v[132:133], v[84:85]
	v_pk_mul_f32 v[122:123], v[134:135], v[86:87]
	v_pk_fma_f32 v[116:117], v[136:137], v[88:89], v[116:117]
	v_pk_fma_f32 v[118:119], v[138:139], v[90:91], v[118:119]
	v_pk_fma_f32 v[120:121], v[140:141], v[92:93], v[120:121]
	v_pk_fma_f32 v[122:123], v[142:143], v[94:95], v[122:123]
	v_pk_fma_f32 v[116:117], v[144:145], v[96:97], v[116:117]
	v_pk_fma_f32 v[118:119], v[146:147], v[98:99], v[118:119]
	v_pk_fma_f32 v[120:121], v[148:149], v[100:101], v[120:121]
	v_pk_fma_f32 v[122:123], v[150:151], v[102:103], v[122:123]
	v_pk_fma_f32 v[116:117], v[152:153], v[104:105], v[116:117]
	v_pk_fma_f32 v[118:119], v[154:155], v[106:107], v[118:119]
	v_pk_fma_f32 v[120:121], v[156:157], v[108:109], v[120:121]
	v_pk_fma_f32 v[122:123], v[158:159], v[110:111], v[122:123]
	v_pk_add_f32 v[116:117], v[116:117], v[118:119]
	v_pk_add_f32 v[120:121], v[120:121], v[122:123]
	v_pk_add_f32 v[116:117], v[116:117], v[120:121]
	v_add_f32_e32 v126, v116, v117
	v_lshl_add_u32 v7, v20, 7, v1
	v_lshl_add_u32 v8, v20, 6, v125
	v_add_f32_dpp v126, v126, v126 quad_perm:[1,0,3,2] row_mask:0xf bank_mask:0xf
	global_load_dwordx4 v[184:187], v7, s[48:49] sc1
	s_nop 0
	v_add_f32_dpp v126, v126, v126 quad_perm:[2,3,0,1] row_mask:0xf bank_mask:0xf
	global_load_dwordx2 v[188:189], v8, s[48:49] sc1
	s_nop 0
	v_add_f32_dpp v126, v126, v126 row_half_mirror row_mask:0xf bank_mask:0xf
	v_cndmask_b32_e64 v12, v12, v126, s[68:69]
	s_waitcnt vmcnt(38)
	v_cvt_scalef32_pk32_f32_fp6 v[128:159], v[190:195], 1.0
	v_pk_mul_f32 v[116:117], v[128:129], v[80:81]
	v_pk_mul_f32 v[118:119], v[130:131], v[82:83]
	v_pk_mul_f32 v[120:121], v[132:133], v[84:85]
	v_pk_mul_f32 v[122:123], v[134:135], v[86:87]
	v_pk_fma_f32 v[116:117], v[136:137], v[88:89], v[116:117]
	v_pk_fma_f32 v[118:119], v[138:139], v[90:91], v[118:119]
	v_pk_fma_f32 v[120:121], v[140:141], v[92:93], v[120:121]
	v_pk_fma_f32 v[122:123], v[142:143], v[94:95], v[122:123]
	v_pk_fma_f32 v[116:117], v[144:145], v[96:97], v[116:117]
	v_pk_fma_f32 v[118:119], v[146:147], v[98:99], v[118:119]
	v_pk_fma_f32 v[120:121], v[148:149], v[100:101], v[120:121]
	v_pk_fma_f32 v[122:123], v[150:151], v[102:103], v[122:123]
	v_pk_fma_f32 v[116:117], v[152:153], v[104:105], v[116:117]
	v_pk_fma_f32 v[118:119], v[154:155], v[106:107], v[118:119]
	v_pk_fma_f32 v[120:121], v[156:157], v[108:109], v[120:121]
	v_pk_fma_f32 v[122:123], v[158:159], v[110:111], v[122:123]
	v_pk_add_f32 v[116:117], v[116:117], v[118:119]
	v_pk_add_f32 v[120:121], v[120:121], v[122:123]
	v_pk_add_f32 v[116:117], v[116:117], v[120:121]
	v_add_f32_e32 v126, v116, v117
	v_lshl_add_u32 v7, v21, 7, v1
	v_lshl_add_u32 v8, v21, 6, v125
	v_add_f32_dpp v126, v126, v126 quad_perm:[1,0,3,2] row_mask:0xf bank_mask:0xf
	global_load_dwordx4 v[190:193], v7, s[48:49] sc1
	s_nop 0
	v_add_f32_dpp v126, v126, v126 quad_perm:[2,3,0,1] row_mask:0xf bank_mask:0xf
	global_load_dwordx2 v[194:195], v8, s[48:49] sc1
	s_nop 0
	v_add_f32_dpp v126, v126, v126 row_half_mirror row_mask:0xf bank_mask:0xf
	v_cndmask_b32_e64 v12, v12, v126, s[70:71]
	s_waitcnt vmcnt(38)
	v_cvt_scalef32_pk32_f32_fp6 v[128:159], v[196:201], 1.0
	v_pk_mul_f32 v[116:117], v[128:129], v[80:81]
	v_pk_mul_f32 v[118:119], v[130:131], v[82:83]
	v_pk_mul_f32 v[120:121], v[132:133], v[84:85]
	v_pk_mul_f32 v[122:123], v[134:135], v[86:87]
	v_pk_fma_f32 v[116:117], v[136:137], v[88:89], v[116:117]
	v_pk_fma_f32 v[118:119], v[138:139], v[90:91], v[118:119]
	v_pk_fma_f32 v[120:121], v[140:141], v[92:93], v[120:121]
	v_pk_fma_f32 v[122:123], v[142:143], v[94:95], v[122:123]
	v_pk_fma_f32 v[116:117], v[144:145], v[96:97], v[116:117]
	v_pk_fma_f32 v[118:119], v[146:147], v[98:99], v[118:119]
	v_pk_fma_f32 v[120:121], v[148:149], v[100:101], v[120:121]
	v_pk_fma_f32 v[122:123], v[150:151], v[102:103], v[122:123]
	v_pk_fma_f32 v[116:117], v[152:153], v[104:105], v[116:117]
	v_pk_fma_f32 v[118:119], v[154:155], v[106:107], v[118:119]
	v_pk_fma_f32 v[120:121], v[156:157], v[108:109], v[120:121]
	v_pk_fma_f32 v[122:123], v[158:159], v[110:111], v[122:123]
	v_pk_add_f32 v[116:117], v[116:117], v[118:119]
	v_pk_add_f32 v[120:121], v[120:121], v[122:123]
	v_pk_add_f32 v[116:117], v[116:117], v[120:121]
	v_add_f32_e32 v126, v116, v117
	v_lshl_add_u32 v7, v22, 7, v1
	v_lshl_add_u32 v8, v22, 6, v125
	v_add_f32_dpp v126, v126, v126 quad_perm:[1,0,3,2] row_mask:0xf bank_mask:0xf
	global_load_dwordx4 v[196:199], v7, s[48:49] sc1
	s_nop 0
	v_add_f32_dpp v126, v126, v126 quad_perm:[2,3,0,1] row_mask:0xf bank_mask:0xf
	global_load_dwordx2 v[200:201], v8, s[48:49] sc1
	s_nop 0
	v_add_f32_dpp v126, v126, v126 row_half_mirror row_mask:0xf bank_mask:0xf
	v_cndmask_b32_e64 v12, v12, v126, s[72:73]
	s_waitcnt vmcnt(38)
	v_cvt_scalef32_pk32_f32_fp6 v[128:159], v[202:207], 1.0
	v_pk_mul_f32 v[116:117], v[128:129], v[80:81]
	v_pk_mul_f32 v[118:119], v[130:131], v[82:83]
	v_pk_mul_f32 v[120:121], v[132:133], v[84:85]
	v_pk_mul_f32 v[122:123], v[134:135], v[86:87]
	v_pk_fma_f32 v[116:117], v[136:137], v[88:89], v[116:117]
	v_pk_fma_f32 v[118:119], v[138:139], v[90:91], v[118:119]
	v_pk_fma_f32 v[120:121], v[140:141], v[92:93], v[120:121]
	v_pk_fma_f32 v[122:123], v[142:143], v[94:95], v[122:123]
	v_pk_fma_f32 v[116:117], v[144:145], v[96:97], v[116:117]
	v_pk_fma_f32 v[118:119], v[146:147], v[98:99], v[118:119]
	v_pk_fma_f32 v[120:121], v[148:149], v[100:101], v[120:121]
	v_pk_fma_f32 v[122:123], v[150:151], v[102:103], v[122:123]
	v_pk_fma_f32 v[116:117], v[152:153], v[104:105], v[116:117]
	v_pk_fma_f32 v[118:119], v[154:155], v[106:107], v[118:119]
	v_pk_fma_f32 v[120:121], v[156:157], v[108:109], v[120:121]
	v_pk_fma_f32 v[122:123], v[158:159], v[110:111], v[122:123]
	v_pk_add_f32 v[116:117], v[116:117], v[118:119]
	v_pk_add_f32 v[120:121], v[120:121], v[122:123]
	v_pk_add_f32 v[116:117], v[116:117], v[120:121]
	v_add_f32_e32 v126, v116, v117
	v_lshl_add_u32 v7, v23, 7, v1
	v_lshl_add_u32 v8, v23, 6, v125
	v_add_f32_dpp v126, v126, v126 quad_perm:[1,0,3,2] row_mask:0xf bank_mask:0xf
	global_load_dwordx4 v[202:205], v7, s[48:49] sc1
	s_nop 0
	v_add_f32_dpp v126, v126, v126 quad_perm:[2,3,0,1] row_mask:0xf bank_mask:0xf
	global_load_dwordx2 v[206:207], v8, s[48:49] sc1
	s_nop 0
	v_add_f32_dpp v126, v126, v126 row_half_mirror row_mask:0xf bank_mask:0xf
	v_cndmask_b32_e64 v12, v12, v126, s[74:75]
	s_waitcnt vmcnt(38)
	v_cvt_scalef32_pk32_f32_fp6 v[128:159], v[208:213], 1.0
	v_pk_mul_f32 v[116:117], v[128:129], v[80:81]
	v_pk_mul_f32 v[118:119], v[130:131], v[82:83]
	v_pk_mul_f32 v[120:121], v[132:133], v[84:85]
	v_pk_mul_f32 v[122:123], v[134:135], v[86:87]
	v_pk_fma_f32 v[116:117], v[136:137], v[88:89], v[116:117]
	v_pk_fma_f32 v[118:119], v[138:139], v[90:91], v[118:119]
	v_pk_fma_f32 v[120:121], v[140:141], v[92:93], v[120:121]
	v_pk_fma_f32 v[122:123], v[142:143], v[94:95], v[122:123]
	v_pk_fma_f32 v[116:117], v[144:145], v[96:97], v[116:117]
	v_pk_fma_f32 v[118:119], v[146:147], v[98:99], v[118:119]
	v_pk_fma_f32 v[120:121], v[148:149], v[100:101], v[120:121]
	v_pk_fma_f32 v[122:123], v[150:151], v[102:103], v[122:123]
	v_pk_fma_f32 v[116:117], v[152:153], v[104:105], v[116:117]
	v_pk_fma_f32 v[118:119], v[154:155], v[106:107], v[118:119]
	v_pk_fma_f32 v[120:121], v[156:157], v[108:109], v[120:121]
	v_pk_fma_f32 v[122:123], v[158:159], v[110:111], v[122:123]
	v_pk_add_f32 v[116:117], v[116:117], v[118:119]
	v_pk_add_f32 v[120:121], v[120:121], v[122:123]
	v_pk_add_f32 v[116:117], v[116:117], v[120:121]
	v_add_f32_e32 v126, v116, v117
	v_lshl_add_u32 v7, v24, 7, v1
	v_lshl_add_u32 v8, v24, 6, v125
	v_add_f32_dpp v126, v126, v126 quad_perm:[1,0,3,2] row_mask:0xf bank_mask:0xf
	global_load_dwordx4 v[208:211], v7, s[48:49] sc1
	s_nop 0
	v_add_f32_dpp v126, v126, v126 quad_perm:[2,3,0,1] row_mask:0xf bank_mask:0xf
	global_load_dwordx2 v[212:213], v8, s[48:49] sc1
	s_nop 0
	v_add_f32_dpp v126, v126, v126 row_half_mirror row_mask:0xf bank_mask:0xf
	v_cndmask_b32_e64 v15, v15, v126, s[60:61]
	s_waitcnt vmcnt(38)
	v_cvt_scalef32_pk32_f32_fp6 v[128:159], v[214:219], 1.0
	v_pk_mul_f32 v[116:117], v[128:129], v[80:81]
	v_pk_mul_f32 v[118:119], v[130:131], v[82:83]
	v_pk_mul_f32 v[120:121], v[132:133], v[84:85]
	v_pk_mul_f32 v[122:123], v[134:135], v[86:87]
	v_pk_fma_f32 v[116:117], v[136:137], v[88:89], v[116:117]
	v_pk_fma_f32 v[118:119], v[138:139], v[90:91], v[118:119]
	v_pk_fma_f32 v[120:121], v[140:141], v[92:93], v[120:121]
	v_pk_fma_f32 v[122:123], v[142:143], v[94:95], v[122:123]
	v_pk_fma_f32 v[116:117], v[144:145], v[96:97], v[116:117]
	v_pk_fma_f32 v[118:119], v[146:147], v[98:99], v[118:119]
	v_pk_fma_f32 v[120:121], v[148:149], v[100:101], v[120:121]
	v_pk_fma_f32 v[122:123], v[150:151], v[102:103], v[122:123]
	v_pk_fma_f32 v[116:117], v[152:153], v[104:105], v[116:117]
	v_pk_fma_f32 v[118:119], v[154:155], v[106:107], v[118:119]
	v_pk_fma_f32 v[120:121], v[156:157], v[108:109], v[120:121]
	v_pk_fma_f32 v[122:123], v[158:159], v[110:111], v[122:123]
	v_pk_add_f32 v[116:117], v[116:117], v[118:119]
	v_pk_add_f32 v[120:121], v[120:121], v[122:123]
	v_pk_add_f32 v[116:117], v[116:117], v[120:121]
	v_add_f32_e32 v126, v116, v117
	v_lshl_add_u32 v7, v25, 7, v1
	v_lshl_add_u32 v8, v25, 6, v125
	v_add_f32_dpp v126, v126, v126 quad_perm:[1,0,3,2] row_mask:0xf bank_mask:0xf
	global_load_dwordx4 v[214:217], v7, s[48:49] sc1
	s_nop 0
	v_add_f32_dpp v126, v126, v126 quad_perm:[2,3,0,1] row_mask:0xf bank_mask:0xf
	global_load_dwordx2 v[218:219], v8, s[48:49] sc1
	s_nop 0
	v_add_f32_dpp v126, v126, v126 row_half_mirror row_mask:0xf bank_mask:0xf
	v_cndmask_b32_e64 v15, v15, v126, s[62:63]
	s_waitcnt vmcnt(38)
	v_cvt_scalef32_pk32_f32_fp6 v[128:159], v[220:225], 1.0
	v_pk_mul_f32 v[116:117], v[128:129], v[80:81]
	v_pk_mul_f32 v[118:119], v[130:131], v[82:83]
	v_pk_mul_f32 v[120:121], v[132:133], v[84:85]
	v_pk_mul_f32 v[122:123], v[134:135], v[86:87]
	v_pk_fma_f32 v[116:117], v[136:137], v[88:89], v[116:117]
	v_pk_fma_f32 v[118:119], v[138:139], v[90:91], v[118:119]
	v_pk_fma_f32 v[120:121], v[140:141], v[92:93], v[120:121]
	v_pk_fma_f32 v[122:123], v[142:143], v[94:95], v[122:123]
	v_pk_fma_f32 v[116:117], v[144:145], v[96:97], v[116:117]
	v_pk_fma_f32 v[118:119], v[146:147], v[98:99], v[118:119]
	v_pk_fma_f32 v[120:121], v[148:149], v[100:101], v[120:121]
	v_pk_fma_f32 v[122:123], v[150:151], v[102:103], v[122:123]
	v_pk_fma_f32 v[116:117], v[152:153], v[104:105], v[116:117]
	v_pk_fma_f32 v[118:119], v[154:155], v[106:107], v[118:119]
	v_pk_fma_f32 v[120:121], v[156:157], v[108:109], v[120:121]
	v_pk_fma_f32 v[122:123], v[158:159], v[110:111], v[122:123]
	v_pk_add_f32 v[116:117], v[116:117], v[118:119]
	v_pk_add_f32 v[120:121], v[120:121], v[122:123]
	v_pk_add_f32 v[116:117], v[116:117], v[120:121]
	v_add_f32_e32 v126, v116, v117
	v_lshl_add_u32 v7, v26, 7, v1
	v_lshl_add_u32 v8, v26, 6, v125
	v_add_f32_dpp v126, v126, v126 quad_perm:[1,0,3,2] row_mask:0xf bank_mask:0xf
	global_load_dwordx4 v[220:223], v7, s[48:49] sc1
	s_nop 0
	v_add_f32_dpp v126, v126, v126 quad_perm:[2,3,0,1] row_mask:0xf bank_mask:0xf
	global_load_dwordx2 v[224:225], v8, s[48:49] sc1
	s_nop 0
	v_add_f32_dpp v126, v126, v126 row_half_mirror row_mask:0xf bank_mask:0xf
	v_cndmask_b32_e64 v15, v15, v126, s[64:65]
	s_waitcnt vmcnt(38)
	v_cvt_scalef32_pk32_f32_fp6 v[128:159], v[226:231], 1.0
	v_pk_mul_f32 v[116:117], v[128:129], v[80:81]
	v_pk_mul_f32 v[118:119], v[130:131], v[82:83]
	v_pk_mul_f32 v[120:121], v[132:133], v[84:85]
	v_pk_mul_f32 v[122:123], v[134:135], v[86:87]
	v_pk_fma_f32 v[116:117], v[136:137], v[88:89], v[116:117]
	v_pk_fma_f32 v[118:119], v[138:139], v[90:91], v[118:119]
	v_pk_fma_f32 v[120:121], v[140:141], v[92:93], v[120:121]
	v_pk_fma_f32 v[122:123], v[142:143], v[94:95], v[122:123]
	v_pk_fma_f32 v[116:117], v[144:145], v[96:97], v[116:117]
	v_pk_fma_f32 v[118:119], v[146:147], v[98:99], v[118:119]
	v_pk_fma_f32 v[120:121], v[148:149], v[100:101], v[120:121]
	v_pk_fma_f32 v[122:123], v[150:151], v[102:103], v[122:123]
	v_pk_fma_f32 v[116:117], v[152:153], v[104:105], v[116:117]
	v_pk_fma_f32 v[118:119], v[154:155], v[106:107], v[118:119]
	v_pk_fma_f32 v[120:121], v[156:157], v[108:109], v[120:121]
	v_pk_fma_f32 v[122:123], v[158:159], v[110:111], v[122:123]
	v_pk_add_f32 v[116:117], v[116:117], v[118:119]
	v_pk_add_f32 v[120:121], v[120:121], v[122:123]
	v_pk_add_f32 v[116:117], v[116:117], v[120:121]
	v_add_f32_e32 v126, v116, v117
	v_lshl_add_u32 v7, v27, 7, v1
	v_lshl_add_u32 v8, v27, 6, v125
	v_add_f32_dpp v126, v126, v126 quad_perm:[1,0,3,2] row_mask:0xf bank_mask:0xf
	global_load_dwordx4 v[226:229], v7, s[48:49] sc1
	s_nop 0
	v_add_f32_dpp v126, v126, v126 quad_perm:[2,3,0,1] row_mask:0xf bank_mask:0xf
	global_load_dwordx2 v[230:231], v8, s[48:49] sc1
	s_nop 0
	v_add_f32_dpp v126, v126, v126 row_half_mirror row_mask:0xf bank_mask:0xf
	v_cndmask_b32_e64 v15, v15, v126, s[66:67]
	s_waitcnt vmcnt(38)
	v_cvt_scalef32_pk32_f32_fp6 v[128:159], v[232:237], 1.0
	v_pk_mul_f32 v[116:117], v[128:129], v[80:81]
	v_pk_mul_f32 v[118:119], v[130:131], v[82:83]
	v_pk_mul_f32 v[120:121], v[132:133], v[84:85]
	v_pk_mul_f32 v[122:123], v[134:135], v[86:87]
	v_pk_fma_f32 v[116:117], v[136:137], v[88:89], v[116:117]
	v_pk_fma_f32 v[118:119], v[138:139], v[90:91], v[118:119]
	v_pk_fma_f32 v[120:121], v[140:141], v[92:93], v[120:121]
	v_pk_fma_f32 v[122:123], v[142:143], v[94:95], v[122:123]
	v_pk_fma_f32 v[116:117], v[144:145], v[96:97], v[116:117]
	v_pk_fma_f32 v[118:119], v[146:147], v[98:99], v[118:119]
	v_pk_fma_f32 v[120:121], v[148:149], v[100:101], v[120:121]
	v_pk_fma_f32 v[122:123], v[150:151], v[102:103], v[122:123]
	v_pk_fma_f32 v[116:117], v[152:153], v[104:105], v[116:117]
	v_pk_fma_f32 v[118:119], v[154:155], v[106:107], v[118:119]
	v_pk_fma_f32 v[120:121], v[156:157], v[108:109], v[120:121]
	v_pk_fma_f32 v[122:123], v[158:159], v[110:111], v[122:123]
	v_pk_add_f32 v[116:117], v[116:117], v[118:119]
	v_pk_add_f32 v[120:121], v[120:121], v[122:123]
	v_pk_add_f32 v[116:117], v[116:117], v[120:121]
	v_add_f32_e32 v126, v116, v117
	v_lshl_add_u32 v7, v28, 7, v1
	v_lshl_add_u32 v8, v28, 6, v125
	v_add_f32_dpp v126, v126, v126 quad_perm:[1,0,3,2] row_mask:0xf bank_mask:0xf
	global_load_dwordx4 v[232:235], v7, s[48:49] sc1
	s_nop 0
	v_add_f32_dpp v126, v126, v126 quad_perm:[2,3,0,1] row_mask:0xf bank_mask:0xf
	global_load_dwordx2 v[236:237], v8, s[48:49] sc1
	s_nop 0
	v_add_f32_dpp v126, v126, v126 row_half_mirror row_mask:0xf bank_mask:0xf
	v_cndmask_b32_e64 v15, v15, v126, s[68:69]
	s_waitcnt vmcnt(38)
	v_cvt_scalef32_pk32_f32_fp6 v[128:159], v[238:243], 1.0
	v_pk_mul_f32 v[116:117], v[128:129], v[80:81]
	v_pk_mul_f32 v[118:119], v[130:131], v[82:83]
	v_pk_mul_f32 v[120:121], v[132:133], v[84:85]
	v_pk_mul_f32 v[122:123], v[134:135], v[86:87]
	v_pk_fma_f32 v[116:117], v[136:137], v[88:89], v[116:117]
	v_pk_fma_f32 v[118:119], v[138:139], v[90:91], v[118:119]
	v_pk_fma_f32 v[120:121], v[140:141], v[92:93], v[120:121]
	v_pk_fma_f32 v[122:123], v[142:143], v[94:95], v[122:123]
	v_pk_fma_f32 v[116:117], v[144:145], v[96:97], v[116:117]
	v_pk_fma_f32 v[118:119], v[146:147], v[98:99], v[118:119]
	v_pk_fma_f32 v[120:121], v[148:149], v[100:101], v[120:121]
	v_pk_fma_f32 v[122:123], v[150:151], v[102:103], v[122:123]
	v_pk_fma_f32 v[116:117], v[152:153], v[104:105], v[116:117]
	v_pk_fma_f32 v[118:119], v[154:155], v[106:107], v[118:119]
	v_pk_fma_f32 v[120:121], v[156:157], v[108:109], v[120:121]
	v_pk_fma_f32 v[122:123], v[158:159], v[110:111], v[122:123]
	v_pk_add_f32 v[116:117], v[116:117], v[118:119]
	v_pk_add_f32 v[120:121], v[120:121], v[122:123]
	v_pk_add_f32 v[116:117], v[116:117], v[120:121]
	v_add_f32_e32 v126, v116, v117
	v_lshl_add_u32 v7, v29, 7, v1
	v_lshl_add_u32 v8, v29, 6, v125
	v_add_f32_dpp v126, v126, v126 quad_perm:[1,0,3,2] row_mask:0xf bank_mask:0xf
	global_load_dwordx4 v[238:241], v7, s[48:49] sc1
	s_nop 0
	v_add_f32_dpp v126, v126, v126 quad_perm:[2,3,0,1] row_mask:0xf bank_mask:0xf
	global_load_dwordx2 v[242:243], v8, s[48:49] sc1
	s_nop 0
	v_add_f32_dpp v126, v126, v126 row_half_mirror row_mask:0xf bank_mask:0xf
	v_cndmask_b32_e64 v15, v15, v126, s[70:71]
	s_waitcnt vmcnt(38)
	v_cvt_scalef32_pk32_f32_fp6 v[128:159], v[244:249], 1.0
	v_pk_mul_f32 v[116:117], v[128:129], v[80:81]
	v_pk_mul_f32 v[118:119], v[130:131], v[82:83]
	v_pk_mul_f32 v[120:121], v[132:133], v[84:85]
	v_pk_mul_f32 v[122:123], v[134:135], v[86:87]
	v_pk_fma_f32 v[116:117], v[136:137], v[88:89], v[116:117]
	v_pk_fma_f32 v[118:119], v[138:139], v[90:91], v[118:119]
	v_pk_fma_f32 v[120:121], v[140:141], v[92:93], v[120:121]
	v_pk_fma_f32 v[122:123], v[142:143], v[94:95], v[122:123]
	v_pk_fma_f32 v[116:117], v[144:145], v[96:97], v[116:117]
	v_pk_fma_f32 v[118:119], v[146:147], v[98:99], v[118:119]
	v_pk_fma_f32 v[120:121], v[148:149], v[100:101], v[120:121]
	v_pk_fma_f32 v[122:123], v[150:151], v[102:103], v[122:123]
	v_pk_fma_f32 v[116:117], v[152:153], v[104:105], v[116:117]
	v_pk_fma_f32 v[118:119], v[154:155], v[106:107], v[118:119]
	v_pk_fma_f32 v[120:121], v[156:157], v[108:109], v[120:121]
	v_pk_fma_f32 v[122:123], v[158:159], v[110:111], v[122:123]
	v_pk_add_f32 v[116:117], v[116:117], v[118:119]
	v_pk_add_f32 v[120:121], v[120:121], v[122:123]
	v_pk_add_f32 v[116:117], v[116:117], v[120:121]
	v_add_f32_e32 v126, v116, v117
	v_lshl_add_u32 v7, v30, 7, v1
	v_lshl_add_u32 v8, v30, 6, v125
	v_add_f32_dpp v126, v126, v126 quad_perm:[1,0,3,2] row_mask:0xf bank_mask:0xf
	global_load_dwordx4 v[244:247], v7, s[48:49] sc1
	s_nop 0
	v_add_f32_dpp v126, v126, v126 quad_perm:[2,3,0,1] row_mask:0xf bank_mask:0xf
	global_load_dwordx2 v[248:249], v8, s[48:49] sc1
	s_nop 0
	v_add_f32_dpp v126, v126, v126 row_half_mirror row_mask:0xf bank_mask:0xf
	v_cndmask_b32_e64 v15, v15, v126, s[72:73]
	s_waitcnt vmcnt(38)
	v_cvt_scalef32_pk32_f32_fp6 v[128:159], v[250:255], 1.0
	v_pk_mul_f32 v[116:117], v[128:129], v[80:81]
	v_pk_mul_f32 v[118:119], v[130:131], v[82:83]
	v_pk_mul_f32 v[120:121], v[132:133], v[84:85]
	v_pk_mul_f32 v[122:123], v[134:135], v[86:87]
	v_pk_fma_f32 v[116:117], v[136:137], v[88:89], v[116:117]
	v_pk_fma_f32 v[118:119], v[138:139], v[90:91], v[118:119]
	v_pk_fma_f32 v[120:121], v[140:141], v[92:93], v[120:121]
	v_pk_fma_f32 v[122:123], v[142:143], v[94:95], v[122:123]
	v_pk_fma_f32 v[116:117], v[144:145], v[96:97], v[116:117]
	v_pk_fma_f32 v[118:119], v[146:147], v[98:99], v[118:119]
	v_pk_fma_f32 v[120:121], v[148:149], v[100:101], v[120:121]
	v_pk_fma_f32 v[122:123], v[150:151], v[102:103], v[122:123]
	v_pk_fma_f32 v[116:117], v[152:153], v[104:105], v[116:117]
	v_pk_fma_f32 v[118:119], v[154:155], v[106:107], v[118:119]
	v_pk_fma_f32 v[120:121], v[156:157], v[108:109], v[120:121]
	v_pk_fma_f32 v[122:123], v[158:159], v[110:111], v[122:123]
	v_pk_add_f32 v[116:117], v[116:117], v[118:119]
	v_pk_add_f32 v[120:121], v[120:121], v[122:123]
	v_pk_add_f32 v[116:117], v[116:117], v[120:121]
	v_add_f32_e32 v126, v116, v117
	v_lshl_add_u32 v7, v31, 7, v1
	v_lshl_add_u32 v8, v31, 6, v125
	v_add_f32_dpp v126, v126, v126 quad_perm:[1,0,3,2] row_mask:0xf bank_mask:0xf
	global_load_dwordx4 v[250:253], v7, s[48:49] sc1
	s_nop 0
	v_add_f32_dpp v126, v126, v126 quad_perm:[2,3,0,1] row_mask:0xf bank_mask:0xf
	global_load_dwordx2 v[254:255], v8, s[48:49] sc1
	s_nop 0
	v_add_f32_dpp v126, v126, v126 row_half_mirror row_mask:0xf bank_mask:0xf
	v_cndmask_b32_e64 v15, v15, v126, s[74:75]
	v_mul_f32_e32 v12, v12, v127
	v_mul_f32_e32 v15, v15, v127
	global_store_dword v9, v12, s[44:45]
	global_store_dword v9, v15, s[44:45] offset:32
	s_add_u32 s28, s28, 1
	s_cmp_lt_u32 s28, 128
	s_cbranch_scc1 .Lpa_tokloop
	s_waitcnt vmcnt(0)
	s_waitcnt vmcnt(0) lgkmcnt(0)
	s_barrier
	s_cmp_lg_u32 s21, 0
	s_cbranch_scc1 .Lpb_skip_g
	s_mov_b64 exec, 1
	v_mov_b32_e32 v10, 0x12000
	ds_read_b32 v12, v10
	ds_read_b32 v13, v10 offset:4
	s_getreg_b32 s44, hwreg(HW_REG_XCC_ID, 0, 4)
	s_and_b32 s44, s44, 15
	s_lshl_b32 s44, s44, 2
	s_waitcnt lgkmcnt(0)
	v_readfirstlane_b32 s45, v12
	v_readfirstlane_b32 s46, v13
	v_mov_b32_e32 v10, s44
	v_mov_b32_e32 v11, 1
	global_atomic_add v12, v10, v11, s[14:15] offset:384 sc0
	s_waitcnt vmcnt(0)
	v_readfirstlane_b32 s47, v12
	s_nop 3
	s_add_u32 s47, s47, 1
	s_cmp_lg_u32 s47, s45
	v_mov_b32_e32 v10, 0
	s_cbranch_scc1 .Lpb_notlast_g
	buffer_wbl2 sc1
	s_waitcnt vmcnt(0)
	global_atomic_add v10, v11, s[14:15] offset:448
	s_waitcnt vmcnt(0)
